# prep conv stage: one 64-bit row address chain per thread (base + k*stride) shared by the three QKV parts through immediate offsets, instead of a 64-bit multiply per load
# baseline (speedup 1.0000x reference)
.LBB0_558:
	s_or_b64 exec, exec, s[0:1]
	v_lshlrev_b32_e32 v150, 3, v148
	v_and_b32_e32 v167, 0x78, v150
	v_ashrrev_i32_e32 v149, 4, v148
	v_lshlrev_b32_e32 v168, 2, v149
	v_lshl_or_b32 v5, v163, 7, v167
	v_add3_u32 v6, v168, v4, -1
	v_lshlrev_b32_e32 v0, 1, v5
	v_add_u32_e32 v0, 0x800, v0
	v_lshl_add_u64 v[2:3], s[38:39], 0, v[0:1]
	v_cmp_gt_u32_e64 s[0:1], s16, v6
	v_add_u32_e32 v8, v4, v168
	v_mov_b32_e32 v9, v1
	v_lshl_add_u64 v[8:9], v[8:9], 0, v[26:27]
	v_mad_u64_u32 v[44:45], s[24:25], v8, s29, v[2:3]
	v_mad_i32_i24 v45, v9, s29, v45
	v_mov_b32_e32 v30, s29
	v_mov_b32_e32 v31, 0
	v_add_u32_e32 v28, 5, v6
	v_sub_co_u32_e32 v42, vcc, v44, v30
	s_nop 0
	v_subbrev_co_u32_e32 v43, vcc, 0, v45, vcc
	v_cmp_gt_u32_e64 s[58:59], s16, v28
	v_lshl_add_u64 v[46:47], v[44:45], 0, v[30:31]
	v_mov_b32_e32 v131, 0
	v_mov_b32_e32 v132, 0
	v_mov_b32_e32 v133, 0
	v_lshl_add_u64 v[48:49], v[46:47], 0, v[30:31]
	s_mov_b64 s[26:27], 0x3000
	s_and_saveexec_b64 s[22:23], s[0:1]
	global_load_dwordx4 v[130:133], v[42:43], off offset:-2048
	s_or_b64 exec, exec, s[22:23]
	v_lshl_add_u64 v[34:35], v[48:49], 0, v[30:31]
	global_load_dwordx4 v[142:145], v[44:45], off offset:-2048
	v_lshl_add_u64 v[36:37], v[34:35], 0, v[30:31]
	global_load_dwordx4 v[138:141], v[46:47], off offset:-2048
	global_load_dwordx4 v[134:137], v[48:49], off offset:-2048
	global_load_dwordx4 v[106:109], v[34:35], off offset:-2048
	v_mov_b32_e32 v82, 0
	v_mov_b32_e32 v98, 0
	v_mov_b32_e32 v99, 0
	v_mov_b32_e32 v100, 0
	v_mov_b32_e32 v101, 0
	s_and_saveexec_b64 s[22:23], s[58:59]
	global_load_dwordx4 v[98:101], v[36:37], off offset:-2048
	s_or_b64 exec, exec, s[22:23]
	v_lshlrev_b32_e32 v0, 2, v5
	v_lshl_add_u64 v[2:3], s[78:79], 0, v[0:1]
	v_add_co_u32_e32 v12, vcc, 0x3000, v2
	v_lshl_add_u64 v[10:11], v[2:3], 0, s[26:27]
	s_nop 0
	v_addc_co_u32_e32 v13, vcc, 0, v3, vcc
	s_mov_b64 s[22:23], 0x6000
	global_load_dwordx4 v[118:121], v0, s[78:79] offset:16
	global_load_dwordx4 v[102:105], v0, s[78:79]
	global_load_dwordx4 v[110:113], v[12:13], off
	global_load_dwordx4 v[122:125], v[10:11], off offset:16
	v_lshl_add_u64 v[10:11], v[2:3], 0, s[22:23]
	v_add_co_u32_e32 v2, vcc, 0x6000, v2
	v_mov_b32_e32 v83, 0
	s_nop 0
	v_addc_co_u32_e32 v3, vcc, 0, v3, vcc
	global_load_dwordx4 v[114:117], v[2:3], off
	global_load_dwordx4 v[126:129], v[10:11], off offset:16
	v_or_b32_e32 v3, 0x400, v5
	v_mov_b32_e32 v84, 0
	v_mov_b32_e32 v85, 0
	s_and_saveexec_b64 s[22:23], s[0:1]
	global_load_dwordx4 v[82:85], v[42:43], off
	s_or_b64 exec, exec, s[22:23]
	global_load_dwordx4 v[94:97], v[44:45], off
	global_load_dwordx4 v[90:93], v[46:47], off
	global_load_dwordx4 v[86:89], v[48:49], off
	global_load_dwordx4 v[54:57], v[34:35], off
	v_mov_b32_e32 v2, 0
	v_mov_b32_e32 v50, 0
	v_mov_b32_e32 v51, 0
	v_mov_b32_e32 v52, 0
	v_mov_b32_e32 v53, 0
	s_and_saveexec_b64 s[22:23], s[58:59]
	global_load_dwordx4 v[50:53], v[36:37], off
	s_or_b64 exec, exec, s[22:23]
	v_lshlrev_b32_e32 v0, 2, v3
	v_lshl_add_u64 v[10:11], s[78:79], 0, v[0:1]
	v_add_co_u32_e32 v18, vcc, 0x3000, v10
	v_lshl_add_u64 v[12:13], v[10:11], 0, s[26:27]
	s_nop 0
	v_addc_co_u32_e32 v19, vcc, 0, v11, vcc
	s_mov_b64 s[22:23], 0x6000
	global_load_dwordx4 v[70:73], v0, s[78:79] offset:16
	global_load_dwordx4 v[58:61], v0, s[78:79]
	global_load_dwordx4 v[62:65], v[18:19], off
	global_load_dwordx4 v[74:77], v[12:13], off offset:16
	v_lshl_add_u64 v[12:13], v[10:11], 0, s[22:23]
	v_add_co_u32_e32 v10, vcc, 0x6000, v10
	v_or_b32_e32 v32, 0x800, v5
	s_nop 0
	v_addc_co_u32_e32 v11, vcc, 0, v11, vcc
	global_load_dwordx4 v[66:69], v[10:11], off
	global_load_dwordx4 v[78:81], v[12:13], off offset:16
	v_mov_b32_e32 v3, 0
	v_mov_b32_e32 v4, 0
	v_mov_b32_e32 v5, 0
	s_and_saveexec_b64 s[22:23], s[0:1]
	global_load_dwordx4 v[2:5], v[42:43], off offset:2048
	s_or_b64 exec, exec, s[22:23]
	global_load_dwordx4 v[10:13], v[44:45], off offset:2048
	s_mov_b64 s[24:25], 0x3000
	global_load_dwordx4 v[6:9], v[46:47], off offset:2048
	global_load_dwordx4 v[18:21], v[48:49], off offset:2048
	global_load_dwordx4 v[14:17], v[34:35], off offset:2048
	v_mov_b32_e32 v22, 0
	v_mov_b32_e32 v23, 0
	v_mov_b32_e32 v24, 0
	v_mov_b32_e32 v25, 0
	s_and_saveexec_b64 s[0:1], s[58:59]
	global_load_dwordx4 v[22:25], v[36:37], off offset:2048
